# 256x128 K-loops (k0/k4/k10): B fragments read two pairs ahead into spare quads so MFMA groups run back to back
# speedup vs baseline: 1.0215x; 1.0098x over previous
.LBB0_179:
	s_waitcnt vmcnt(5)
	ds_write_b128 v187, v[120:123]
	ds_write_b128 v187, v[136:139] offset:4096
	ds_write_b128 v187, v[140:143] offset:8192
	ds_write_b128 v187, v[144:147] offset:12288
	ds_write_b128 v187, v[148:151] offset:16384
	ds_write_b128 v187, v[152:155] offset:20480
	s_waitcnt vmcnt(4)
	ds_write_b128 v187, v[156:159] offset:24576
	s_waitcnt vmcnt(3)
	ds_write_b128 v187, v[160:163] offset:28672
	ds_write_b128 v187, v[132:135] offset:32768
	s_waitcnt vmcnt(2)
	ds_write_b128 v187, v[164:167] offset:36864
	s_waitcnt vmcnt(1)
	ds_write_b128 v187, v[168:171] offset:40960
	s_waitcnt vmcnt(0)
	ds_write_b128 v187, v[172:175] offset:45056
	v_add_u32_e32 v148, v176, v184
	s_waitcnt lgkmcnt(0)
	s_barrier
	v_add_u32_e32 v152, v176, v185
	ds_read_b128 v[120:123], v148 offset:32768
	ds_read_b128 v[132:135], v148 offset:34816
	ds_read_b128 v[136:139], v152
	ds_read_b128 v[140:143], v152 offset:2048
	ds_read_b128 v[144:147], v148 offset:36864
	ds_read_b128 v[148:151], v148 offset:38912
	ds_read_b128 v[230:233], v152 offset:4096
	ds_read_b128 v[234:237], v152 offset:6144
	ds_read_b128 v[238:241], v152 offset:8192
	ds_read_b128 v[242:245], v152 offset:10240
	s_waitcnt lgkmcnt(7)
	v_mfma_f32_16x16x32_bf16 v[128:131], v[120:123], v[136:139], v[128:131]
	v_add_u32_e32 v156, v186, v185
	s_min_i32 s13, s11, 15
	s_lshl_b32 s56, s13, 7
	v_mfma_f32_16x16x32_bf16 v[108:111], v[132:135], v[136:139], v[108:111]
	s_add_i32 s11, s11, 1
	s_cmp_lg_u32 s11, 17
	s_waitcnt lgkmcnt(5)
	v_mfma_f32_16x16x32_bf16 v[92:95], v[144:147], v[136:139], v[92:95]
	s_waitcnt lgkmcnt(4)
	v_mfma_f32_16x16x32_bf16 v[76:79], v[148:151], v[136:139], v[76:79]
	v_mfma_f32_16x16x32_bf16 v[124:127], v[120:123], v[140:143], v[124:127]
	v_mfma_f32_16x16x32_bf16 v[104:107], v[132:135], v[140:143], v[104:107]
	v_mfma_f32_16x16x32_bf16 v[88:91], v[144:147], v[140:143], v[88:91]
	v_mfma_f32_16x16x32_bf16 v[72:75], v[148:151], v[140:143], v[72:75]
	ds_read_b128 v[136:139], v152 offset:12288
	ds_read_b128 v[140:143], v152 offset:14336
	s_waitcnt lgkmcnt(5)
	v_mfma_f32_16x16x32_bf16 v[116:119], v[120:123], v[230:233], v[116:119]
	v_mfma_f32_16x16x32_bf16 v[100:103], v[132:135], v[230:233], v[100:103]
	v_mfma_f32_16x16x32_bf16 v[84:87], v[144:147], v[230:233], v[84:87]
	v_mfma_f32_16x16x32_bf16 v[68:71], v[148:151], v[230:233], v[68:71]
	s_waitcnt lgkmcnt(4)
	v_mfma_f32_16x16x32_bf16 v[112:115], v[120:123], v[234:237], v[112:115]
	v_mfma_f32_16x16x32_bf16 v[96:99], v[132:135], v[234:237], v[96:99]
	v_mfma_f32_16x16x32_bf16 v[80:83], v[144:147], v[234:237], v[80:83]
	v_mfma_f32_16x16x32_bf16 v[64:67], v[148:151], v[234:237], v[64:67]
	s_waitcnt lgkmcnt(3)
	v_mfma_f32_16x16x32_bf16 v[60:63], v[120:123], v[238:241], v[60:63]
	v_mfma_f32_16x16x32_bf16 v[44:47], v[132:135], v[238:241], v[44:47]
	v_mfma_f32_16x16x32_bf16 v[28:31], v[144:147], v[238:241], v[28:31]
	v_mfma_f32_16x16x32_bf16 v[8:11], v[148:151], v[238:241], v[8:11]
	s_waitcnt lgkmcnt(2)
	v_mfma_f32_16x16x32_bf16 v[56:59], v[120:123], v[242:245], v[56:59]
	v_mfma_f32_16x16x32_bf16 v[40:43], v[132:135], v[242:245], v[40:43]
	v_mfma_f32_16x16x32_bf16 v[24:27], v[144:147], v[242:245], v[24:27]
	v_mfma_f32_16x16x32_bf16 v[4:7], v[148:151], v[242:245], v[4:7]
	s_waitcnt lgkmcnt(1)
	v_mfma_f32_16x16x32_bf16 v[52:55], v[120:123], v[136:139], v[52:55]
	v_mfma_f32_16x16x32_bf16 v[36:39], v[132:135], v[136:139], v[36:39]
	v_mfma_f32_16x16x32_bf16 v[20:23], v[144:147], v[136:139], v[20:23]
	v_mfma_f32_16x16x32_bf16 v[0:3], v[148:151], v[136:139], v[0:3]
	v_add_u32_e32 v136, v186, v184
	ds_read_b128 v[152:155], v136 offset:32768
	ds_read_b128 v[160:163], v136 offset:34816
	s_waitcnt lgkmcnt(2)
	v_mfma_f32_16x16x32_bf16 v[48:51], v[120:123], v[140:143], v[48:51]
	v_mfma_f32_16x16x32_bf16 v[32:35], v[132:135], v[140:143], v[32:35]
	ds_read_b128 v[120:123], v156
	ds_read_b128 v[132:135], v156 offset:2048
	ds_read_b128 v[172:175], v136 offset:36864
	ds_read_b128 v[188:191], v136 offset:38912
	ds_read_b128 v[230:233], v156 offset:4096
	ds_read_b128 v[234:237], v156 offset:6144
	s_waitcnt lgkmcnt(5)
	v_mfma_f32_16x16x32_bf16 v[128:131], v[152:155], v[120:123], v[128:131]
	v_mfma_f32_16x16x32_bf16 v[108:111], v[160:163], v[120:123], v[108:111]
	s_waitcnt lgkmcnt(3)
	v_mfma_f32_16x16x32_bf16 v[92:95], v[172:175], v[120:123], v[92:95]
	s_waitcnt lgkmcnt(2)
	v_mfma_f32_16x16x32_bf16 v[76:79], v[188:191], v[120:123], v[76:79]
	v_mfma_f32_16x16x32_bf16 v[124:127], v[152:155], v[132:135], v[124:127]
	v_mfma_f32_16x16x32_bf16 v[104:107], v[160:163], v[132:135], v[104:107]
	v_mfma_f32_16x16x32_bf16 v[88:91], v[172:175], v[132:135], v[88:91]
	v_mfma_f32_16x16x32_bf16 v[72:75], v[188:191], v[132:135], v[72:75]
	s_waitcnt lgkmcnt(0)
	v_mfma_f32_16x16x32_bf16 v[112:115], v[152:155], v[234:237], v[112:115]
	v_mfma_f32_16x16x32_bf16 v[96:99], v[160:163], v[234:237], v[96:99]
	v_mfma_f32_16x16x32_bf16 v[80:83], v[172:175], v[234:237], v[80:83]
	v_mfma_f32_16x16x32_bf16 v[64:67], v[188:191], v[234:237], v[64:67]
	v_lshl_add_u64 v[132:133], v[178:179], 0, s[56:57]
	v_mfma_f32_16x16x32_bf16 v[12:15], v[148:151], v[140:143], v[12:15]
	v_add_co_u32_e32 v150, vcc, s65, v132
	v_lshl_add_u64 v[148:149], v[180:181], 0, s[56:57]
	s_nop 0
	v_addc_co_u32_e32 v151, vcc, 0, v133, vcc
	v_mfma_f32_16x16x32_bf16 v[16:19], v[144:147], v[140:143], v[16:19]
	ds_read_b128 v[136:139], v156 offset:8192
	ds_read_b128 v[140:143], v156 offset:10240
	ds_read_b128 v[144:147], v156 offset:12288
	ds_read_b128 v[220:223], v156 offset:14336
	v_add_co_u32_e32 v156, vcc, s46, v132
	v_mfma_f32_16x16x32_bf16 v[116:119], v[152:155], v[230:233], v[116:119]
	s_nop 0
	v_addc_co_u32_e32 v157, vcc, 0, v133, vcc
	v_add_co_u32_e32 v158, vcc, s47, v132
	v_mfma_f32_16x16x32_bf16 v[100:103], v[160:163], v[230:233], v[100:103]
	s_nop 0
	v_addc_co_u32_e32 v159, vcc, 0, v133, vcc
	v_add_co_u32_e32 v164, vcc, s33, v132
	v_mfma_f32_16x16x32_bf16 v[84:87], v[172:175], v[230:233], v[84:87]
	s_nop 0
	v_addc_co_u32_e32 v165, vcc, 0, v133, vcc
	v_add_co_u32_e32 v166, vcc, s14, v132
	v_mfma_f32_16x16x32_bf16 v[68:71], v[188:191], v[230:233], v[68:71]
	s_nop 0
	v_addc_co_u32_e32 v167, vcc, 0, v133, vcc
	v_add_co_u32_e32 v168, vcc, s48, v132
	s_waitcnt lgkmcnt(3)
	v_mfma_f32_16x16x32_bf16 v[60:63], v[152:155], v[136:139], v[60:63]
	v_addc_co_u32_e32 v169, vcc, 0, v133, vcc
	v_add_co_u32_e32 v170, vcc, s15, v132
	global_load_dwordx4 v[120:123], v[132:133], off
	s_nop 0
	v_addc_co_u32_e32 v171, vcc, 0, v133, vcc
	v_add_co_u32_e32 v224, vcc, s65, v148
	v_mfma_f32_16x16x32_bf16 v[44:47], v[160:163], v[136:139], v[44:47]
	s_nop 0
	v_addc_co_u32_e32 v225, vcc, 0, v149, vcc
	v_add_co_u32_e32 v226, vcc, s46, v148
	v_mfma_f32_16x16x32_bf16 v[28:31], v[172:175], v[136:139], v[28:31]
	s_nop 0
	v_addc_co_u32_e32 v227, vcc, 0, v149, vcc
	v_add_co_u32_e32 v228, vcc, s47, v148
	v_mfma_f32_16x16x32_bf16 v[8:11], v[188:191], v[136:139], v[8:11]
	global_load_dwordx4 v[132:135], v[148:149], off
	v_addc_co_u32_e32 v229, vcc, 0, v149, vcc
	s_waitcnt lgkmcnt(2)
	v_mfma_f32_16x16x32_bf16 v[56:59], v[152:155], v[140:143], v[56:59]
	v_mfma_f32_16x16x32_bf16 v[40:43], v[160:163], v[140:143], v[40:43]
	v_mfma_f32_16x16x32_bf16 v[24:27], v[172:175], v[140:143], v[24:27]
	v_mfma_f32_16x16x32_bf16 v[4:7], v[188:191], v[140:143], v[4:7]
	s_waitcnt lgkmcnt(1)
	v_mfma_f32_16x16x32_bf16 v[52:55], v[152:155], v[144:147], v[52:55]
	v_mfma_f32_16x16x32_bf16 v[36:39], v[160:163], v[144:147], v[36:39]
	v_mfma_f32_16x16x32_bf16 v[20:23], v[172:175], v[144:147], v[20:23]
	v_mfma_f32_16x16x32_bf16 v[0:3], v[188:191], v[144:147], v[0:3]
	global_load_dwordx4 v[136:139], v[150:151], off
	global_load_dwordx4 v[140:143], v[156:157], off
	global_load_dwordx4 v[144:147], v[158:159], off
	s_waitcnt lgkmcnt(0)
	v_mfma_f32_16x16x32_bf16 v[48:51], v[152:155], v[220:223], v[48:51]
	global_load_dwordx4 v[148:151], v[164:165], off
	global_load_dwordx4 v[152:155], v[166:167], off
	global_load_dwordx4 v[156:159], v[168:169], off
	v_mfma_f32_16x16x32_bf16 v[32:35], v[160:163], v[220:223], v[32:35]
	global_load_dwordx4 v[160:163], v[170:171], off
	global_load_dwordx4 v[164:167], v[224:225], off
	s_nop 0
	global_load_dwordx4 v[168:171], v[226:227], off
	v_mfma_f32_16x16x32_bf16 v[16:19], v[172:175], v[220:223], v[16:19]
	global_load_dwordx4 v[172:175], v[228:229], off
	s_barrier
	v_mfma_f32_16x16x32_bf16 v[12:15], v[188:191], v[220:223], v[12:15]
	s_cbranch_scc1 .LBB0_179
	s_waitcnt vmcnt(11)
	v_mov_b32_e32 v121, v192
	s_lshl_b32 s10, s10, 7
	s_waitcnt vmcnt(10)
	v_and_b32_e32 v134, 64, v121
	v_lshrrev_b32_e32 v121, 2, v121
	v_and_b32_e32 v121, 12, v121
	v_or3_b32 v122, s10, v121, v134
	v_ashrrev_i32_e32 v123, 31, v122
	v_lshl_add_u64 v[132:133], v[122:123], 2, s[0:1]
	global_load_dwordx4 v[136:139], v[132:133], off
	v_lshl_add_u32 v120, s12, 8, v183
	s_ashr_i32 s11, s10, 31
	s_lshl_b64 s[12:13], s[10:11], 1
	v_lshlrev_b32_e32 v176, 1, v134
	s_movk_i32 s11, 0x70
	s_add_i32 s24, s24, s18
	s_cmp_ge_i32 s24, s21
	s_waitcnt vmcnt(0)
	v_pk_add_f32 v[122:123], v[130:131], v[138:139]
	v_pk_add_f32 v[128:129], v[128:129], v[136:137]
	v_max_f32_e32 v122, 0, v122
	v_max_f32_e32 v121, 0, v128
	v_mul_f32_e32 v121, v121, v121
	v_max_f32_e32 v128, 0, v129
	v_mul_f32_e32 v129, v122, v122
	v_max_f32_e32 v122, 0, v123
	v_pk_add_f32 v[126:127], v[126:127], v[138:139]
	v_pk_add_f32 v[124:125], v[124:125], v[136:137]
	v_mul_f32_e32 v128, v128, v128
	v_mul_f32_e32 v123, v122, v122
	s_nop 1
	v_cvt_pk_bf16_f32 v122, v121, v128
	v_max_f32_e32 v121, 0, v124
	v_max_f32_e32 v124, 0, v125
	v_max_f32_e32 v125, 0, v126
	v_max_f32_e32 v126, 0, v127
	v_mul_f32_e32 v125, v125, v125
	v_mul_f32_e32 v126, v126, v126
	s_nop 1
	v_cvt_pk_bf16_f32 v123, v129, v123
	s_nop 1
	v_cvt_pk_bf16_f32 v125, v125, v126
	global_load_dwordx4 v[126:129], v[132:133], off offset:64
	v_mul_f32_e32 v121, v121, v121
	v_mul_f32_e32 v124, v124, v124
	s_nop 1
	v_cvt_pk_bf16_f32 v124, v121, v124
	v_pk_add_f32 v[116:117], v[116:117], v[136:137]
	v_pk_add_f32 v[112:113], v[112:113], v[136:137]
	v_ashrrev_i32_e32 v121, 31, v120
	v_pk_add_f32 v[118:119], v[118:119], v[138:139]
	v_max_f32_e32 v116, 0, v116
	v_max_f32_e32 v117, 0, v117
	v_pk_add_f32 v[114:115], v[114:115], v[138:139]
	v_max_f32_e32 v112, 0, v112
	v_max_f32_e32 v113, 0, v113
	v_mul_f32_e32 v116, v116, v116
	v_mul_f32_e32 v117, v117, v117
	v_max_f32_e32 v118, 0, v118
	v_max_f32_e32 v119, 0, v119
	v_mul_f32_e32 v112, v112, v112
	v_mul_f32_e32 v113, v113, v113
	v_max_f32_e32 v114, 0, v114
	v_max_f32_e32 v115, 0, v115
	v_mul_f32_e32 v118, v118, v118
	v_mul_f32_e32 v119, v119, v119
	s_nop 1
	v_cvt_pk_bf16_f32 v116, v116, v117
	s_nop 1
	v_cvt_pk_bf16_f32 v117, v118, v119
	v_mul_f32_e32 v114, v114, v114
	v_mul_f32_e32 v115, v115, v115
	s_nop 1
	v_cvt_pk_bf16_f32 v112, v112, v113
	s_nop 1
	v_cvt_pk_bf16_f32 v113, v114, v115
	s_waitcnt vmcnt(0)
	v_pk_add_f32 v[110:111], v[110:111], v[128:129]
	v_pk_add_f32 v[108:109], v[108:109], v[126:127]
	v_pk_add_f32 v[106:107], v[106:107], v[128:129]
	v_pk_add_f32 v[104:105], v[104:105], v[126:127]
	v_pk_add_f32 v[102:103], v[102:103], v[128:129]
	v_pk_add_f32 v[100:101], v[100:101], v[126:127]
	v_pk_add_f32 v[98:99], v[98:99], v[128:129]
	v_pk_add_f32 v[96:97], v[96:97], v[126:127]
	global_load_dwordx4 v[126:129], v[132:133], off offset:128
	v_max_f32_e32 v108, 0, v108
	v_max_f32_e32 v109, 0, v109
	v_max_f32_e32 v104, 0, v104
	v_max_f32_e32 v105, 0, v105
	v_max_f32_e32 v100, 0, v100
	v_max_f32_e32 v101, 0, v101
	v_max_f32_e32 v96, 0, v96
	v_max_f32_e32 v97, 0, v97
	v_mul_f32_e32 v108, v108, v108
	v_mul_f32_e32 v109, v109, v109
	v_max_f32_e32 v110, 0, v110
	v_max_f32_e32 v111, 0, v111
	v_mul_f32_e32 v104, v104, v104
	v_mul_f32_e32 v105, v105, v105
	v_max_f32_e32 v106, 0, v106
	v_max_f32_e32 v107, 0, v107
	v_mul_f32_e32 v100, v100, v100
	v_mul_f32_e32 v101, v101, v101
	v_max_f32_e32 v102, 0, v102
	v_max_f32_e32 v103, 0, v103
	v_mul_f32_e32 v96, v96, v96
	v_mul_f32_e32 v97, v97, v97
	v_max_f32_e32 v98, 0, v98
	v_max_f32_e32 v99, 0, v99
	v_mul_f32_e32 v110, v110, v110
	v_mul_f32_e32 v111, v111, v111
	s_nop 1
	v_cvt_pk_bf16_f32 v108, v108, v109
	s_nop 1
	v_cvt_pk_bf16_f32 v109, v110, v111
	v_mul_f32_e32 v106, v106, v106
	v_mul_f32_e32 v107, v107, v107
	s_nop 1
	v_cvt_pk_bf16_f32 v104, v104, v105
	s_nop 1
	v_cvt_pk_bf16_f32 v105, v106, v107
	v_mul_f32_e32 v102, v102, v102
	v_mul_f32_e32 v103, v103, v103
	s_nop 1
	v_cvt_pk_bf16_f32 v100, v100, v101
	s_nop 1
	v_cvt_pk_bf16_f32 v101, v102, v103
	v_mul_f32_e32 v98, v98, v98
	v_mul_f32_e32 v99, v99, v99
	s_nop 1
	v_cvt_pk_bf16_f32 v96, v96, v97
	s_nop 1
	v_cvt_pk_bf16_f32 v97, v98, v99
	s_waitcnt vmcnt(0)
	v_pk_add_f32 v[86:87], v[86:87], v[128:129]
	v_pk_add_f32 v[84:85], v[84:85], v[126:127]
	v_pk_add_f32 v[82:83], v[82:83], v[128:129]
	v_pk_add_f32 v[80:81], v[80:81], v[126:127]
	v_max_f32_e32 v84, 0, v84
	v_max_f32_e32 v85, 0, v85
	v_max_f32_e32 v86, 0, v86
	v_max_f32_e32 v87, 0, v87
	v_max_f32_e32 v80, 0, v80
	v_max_f32_e32 v81, 0, v81
	v_max_f32_e32 v82, 0, v82
	v_max_f32_e32 v83, 0, v83
	v_mul_f32_e32 v84, v84, v84
	v_mul_f32_e32 v85, v85, v85
	v_mul_f32_e32 v86, v86, v86
	v_mul_f32_e32 v87, v87, v87
	v_mul_f32_e32 v80, v80, v80
	v_mul_f32_e32 v81, v81, v81
	v_mul_f32_e32 v82, v82, v82
	v_mul_f32_e32 v83, v83, v83
	s_nop 1
	v_cvt_pk_bf16_f32 v84, v84, v85
	s_nop 1
	v_cvt_pk_bf16_f32 v85, v86, v87
	s_nop 1
	v_cvt_pk_bf16_f32 v86, v80, v81
	s_nop 1
	v_cvt_pk_bf16_f32 v87, v82, v83
	global_load_dwordx4 v[80:83], v[132:133], off offset:192
	v_pk_add_f32 v[92:93], v[92:93], v[126:127]
	v_pk_add_f32 v[88:89], v[88:89], v[126:127]
	v_pk_add_f32 v[94:95], v[94:95], v[128:129]
	v_max_f32_e32 v92, 0, v92
	v_max_f32_e32 v93, 0, v93
	v_pk_add_f32 v[90:91], v[90:91], v[128:129]
	v_max_f32_e32 v88, 0, v88
	v_max_f32_e32 v89, 0, v89
	v_mul_f32_e32 v92, v92, v92
	v_mul_f32_e32 v93, v93, v93
	v_max_f32_e32 v94, 0, v94
	v_max_f32_e32 v95, 0, v95
	v_mul_f32_e32 v88, v88, v88
	v_mul_f32_e32 v89, v89, v89
	v_max_f32_e32 v90, 0, v90
	v_max_f32_e32 v91, 0, v91
	v_mul_f32_e32 v94, v94, v94
	v_mul_f32_e32 v95, v95, v95
	s_nop 1
	v_cvt_pk_bf16_f32 v92, v92, v93
	s_nop 1
	v_cvt_pk_bf16_f32 v93, v94, v95
	v_mul_f32_e32 v90, v90, v90
	v_mul_f32_e32 v91, v91, v91
	s_nop 1
	v_cvt_pk_bf16_f32 v88, v88, v89
	s_nop 1
	v_cvt_pk_bf16_f32 v89, v90, v91
	s_waitcnt vmcnt(0)
	v_pk_add_f32 v[74:75], v[74:75], v[82:83]
	v_pk_add_f32 v[72:73], v[72:73], v[80:81]
	v_max_f32_e32 v74, 0, v74
	v_max_f32_e32 v72, 0, v72
	v_max_f32_e32 v73, 0, v73
	v_mul_f32_e32 v72, v72, v72
	v_mul_f32_e32 v73, v73, v73
	v_mul_f32_e32 v74, v74, v74
	v_max_f32_e32 v75, 0, v75
	v_pk_add_f32 v[70:71], v[70:71], v[82:83]
	v_pk_add_f32 v[68:69], v[68:69], v[80:81]
	v_pk_add_f32 v[78:79], v[78:79], v[82:83]
	v_pk_add_f32 v[76:77], v[76:77], v[80:81]
	v_mul_f32_e32 v75, v75, v75
	s_nop 1
	v_cvt_pk_bf16_f32 v72, v72, v73
	s_nop 1
	v_cvt_pk_bf16_f32 v73, v74, v75
	v_max_f32_e32 v68, 0, v68
	v_max_f32_e32 v69, 0, v69
	v_max_f32_e32 v70, 0, v70
	v_max_f32_e32 v71, 0, v71
	v_pk_add_f32 v[66:67], v[66:67], v[82:83]
	v_pk_add_f32 v[64:65], v[64:65], v[80:81]
	v_mov_b32_e32 v74, v192
	v_max_f32_e32 v76, 0, v76
	v_max_f32_e32 v77, 0, v77
	v_max_f32_e32 v78, 0, v78
	v_max_f32_e32 v79, 0, v79
	v_mul_f32_e32 v68, v68, v68
	v_mul_f32_e32 v69, v69, v69
	v_mul_f32_e32 v70, v70, v70
	v_mul_f32_e32 v71, v71, v71
	v_max_f32_e32 v64, 0, v64
	v_max_f32_e32 v65, 0, v65
	v_max_f32_e32 v66, 0, v66
	v_max_f32_e32 v67, 0, v67
	v_mul_f32_e32 v76, v76, v76
	v_lshlrev_b32_e32 v75, 7, v74
	v_mul_f32_e32 v77, v77, v77
	v_mul_f32_e32 v78, v78, v78
	v_mul_f32_e32 v79, v79, v79
	s_nop 1
	v_cvt_pk_bf16_f32 v68, v68, v69
	s_nop 1
	v_cvt_pk_bf16_f32 v69, v70, v71
	v_mul_f32_e32 v64, v64, v64
	v_mul_f32_e32 v65, v65, v65
	v_mul_f32_e32 v66, v66, v66
	v_mul_f32_e32 v67, v67, v67
	v_and_b32_e32 v70, 15, v74
	v_bfe_u32 v71, v74, 4, 2
	v_and_b32_e32 v75, 0xffffe000, v75
	s_nop 1
	v_cvt_pk_bf16_f32 v76, v76, v77
	s_nop 1
	v_cvt_pk_bf16_f32 v77, v78, v79
	s_nop 1
	v_cvt_pk_bf16_f32 v64, v64, v65
	s_nop 1
	v_cvt_pk_bf16_f32 v65, v66, v67
	v_lshlrev_b64 v[66:67], 13, v[120:121]
	v_lshl_or_b32 v78, v70, 7, v75
	v_bitop3_b32 v79, v71, v74, 15 bitop3:0x78
	v_lshl_add_u64 v[66:67], s[4:5], 0, v[66:67]
	v_lshl_or_b32 v79, v79, 3, v78
	v_bitop3_b32 v80, v71, v70, 4 bitop3:0x36
	v_bitop3_b32 v81, v71, v70, 8 bitop3:0x36
	v_bitop3_b32 v70, v71, v70, 12 bitop3:0x36
	v_lshl_add_u64 v[66:67], v[66:67], 0, s[12:13]
	v_lshl_or_b32 v80, v80, 3, v78
	v_lshl_or_b32 v81, v81, 3, v78
	v_lshl_or_b32 v70, v70, 3, v78
	ds_write2st64_b64 v79, v[122:123], v[124:125] offset1:4
	ds_write2st64_b64 v80, v[108:109], v[104:105] offset1:4
	ds_write2st64_b64 v81, v[92:93], v[88:89] offset1:4
	ds_write2st64_b64 v70, v[76:77], v[72:73] offset1:4
	ds_write2st64_b64 v79, v[116:117], v[112:113] offset0:8 offset1:12
	ds_write2st64_b64 v80, v[100:101], v[96:97] offset0:8 offset1:12
	ds_write2st64_b64 v81, v[84:85], v[86:87] offset0:8 offset1:12
	ds_write2st64_b64 v70, v[68:69], v[64:65] offset0:8 offset1:12
	v_lshlrev_b32_e32 v68, 4, v74
	v_lshl_add_u64 v[66:67], v[66:67], 0, v[176:177]
	v_and_b32_e32 v64, 8, v74
	v_and_b32_e32 v176, 0x70, v68
	v_bfe_u32 v72, v74, 3, 3
	v_cmp_eq_u32_e32 vcc, 0, v64
	v_lshl_add_u64 v[64:65], v[66:67], 0, v[176:177]
	v_and_b32_e32 v67, 48, v74
	v_lshlrev_b32_e32 v66, 7, v72
	v_bitop3_b32 v73, v68, v67, s11 bitop3:0x6c
	v_or3_b32 v66, v75, v66, v73
	ds_read_b128 v[66:69], v66
	v_lshlrev_b32_e32 v176, 13, v72
	v_or_b32_e32 v76, 8, v72
	s_waitcnt lgkmcnt(0)
	v_cndmask_b32_e32 v71, v67, v69, vcc
	v_cndmask_b32_e32 v70, v66, v68, vcc
	v_cndmask_b32_e32 v69, v69, v67, vcc
	v_cndmask_b32_e32 v68, v68, v66, vcc
	v_lshl_add_u64 v[66:67], v[64:65], 0, v[176:177]
	global_store_dwordx4 v[66:67], v[68:71], off
	v_lshrrev_b32_e32 v67, 1, v76
	v_xor_b32_e32 v67, v67, v74
	v_lshlrev_b32_e32 v67, 4, v67
	v_lshlrev_b32_e32 v66, 7, v76
	v_and_b32_e32 v67, 0x70, v67
	v_or3_b32 v66, v75, v66, v67
	ds_read_b128 v[66:69], v66
	v_lshlrev_b32_e32 v176, 13, v76
	v_or_b32_e32 v76, 16, v72
	s_waitcnt lgkmcnt(0)
	v_cndmask_b32_e32 v71, v67, v69, vcc
	v_cndmask_b32_e32 v70, v66, v68, vcc
	v_cndmask_b32_e32 v69, v69, v67, vcc
	v_cndmask_b32_e32 v68, v68, v66, vcc
	v_lshl_add_u64 v[66:67], v[64:65], 0, v[176:177]
	global_store_dwordx4 v[66:67], v[68:71], off
	v_lshlrev_b32_e32 v66, 7, v76
	v_or3_b32 v66, v75, v66, v73
	ds_read_b128 v[66:69], v66
	v_lshlrev_b32_e32 v176, 13, v76
	v_or_b32_e32 v76, 24, v72
	s_waitcnt lgkmcnt(0)
	v_cndmask_b32_e32 v71, v67, v69, vcc
	v_cndmask_b32_e32 v70, v66, v68, vcc
	v_cndmask_b32_e32 v69, v69, v67, vcc
	v_cndmask_b32_e32 v68, v68, v66, vcc
	v_lshl_add_u64 v[66:67], v[64:65], 0, v[176:177]
	global_store_dwordx4 v[66:67], v[68:71], off
	v_lshrrev_b32_e32 v67, 1, v76
	v_xor_b32_e32 v67, v67, v74
	v_lshlrev_b32_e32 v67, 4, v67
	v_lshlrev_b32_e32 v66, 7, v76
	v_and_b32_e32 v67, 0x70, v67
	v_or3_b32 v66, v75, v66, v67
	ds_read_b128 v[66:69], v66
	v_lshlrev_b32_e32 v176, 13, v76
	v_or_b32_e32 v76, 32, v72
	s_waitcnt lgkmcnt(0)
	v_cndmask_b32_e32 v71, v67, v69, vcc
	v_cndmask_b32_e32 v70, v66, v68, vcc
	v_cndmask_b32_e32 v69, v69, v67, vcc
	v_cndmask_b32_e32 v68, v68, v66, vcc
	v_lshl_add_u64 v[66:67], v[64:65], 0, v[176:177]
	global_store_dwordx4 v[66:67], v[68:71], off
	v_lshlrev_b32_e32 v66, 7, v76
	v_or3_b32 v66, v75, v66, v73
	ds_read_b128 v[66:69], v66
	v_lshlrev_b32_e32 v176, 13, v76
	v_or_b32_e32 v76, 40, v72
	s_waitcnt lgkmcnt(0)
	v_cndmask_b32_e32 v71, v67, v69, vcc
	v_cndmask_b32_e32 v70, v66, v68, vcc
	v_cndmask_b32_e32 v69, v69, v67, vcc
	v_cndmask_b32_e32 v68, v68, v66, vcc
	v_lshl_add_u64 v[66:67], v[64:65], 0, v[176:177]
	global_store_dwordx4 v[66:67], v[68:71], off
	v_lshrrev_b32_e32 v67, 1, v76
	v_xor_b32_e32 v67, v67, v74
	v_lshlrev_b32_e32 v67, 4, v67
	v_lshlrev_b32_e32 v66, 7, v76
	v_and_b32_e32 v67, 0x70, v67
	v_or3_b32 v66, v75, v66, v67
	ds_read_b128 v[66:69], v66
	v_lshlrev_b32_e32 v176, 13, v76
	v_or_b32_e32 v76, 48, v72
	v_or_b32_e32 v72, 56, v72
	s_waitcnt lgkmcnt(0)
	v_cndmask_b32_e32 v71, v67, v69, vcc
	v_cndmask_b32_e32 v70, v66, v68, vcc
	v_cndmask_b32_e32 v69, v69, v67, vcc
	v_cndmask_b32_e32 v68, v68, v66, vcc
	v_lshl_add_u64 v[66:67], v[64:65], 0, v[176:177]
	global_store_dwordx4 v[66:67], v[68:71], off
	v_lshlrev_b32_e32 v66, 7, v76
	v_or3_b32 v66, v75, v66, v73
	ds_read_b128 v[66:69], v66
	v_lshlrev_b32_e32 v176, 13, v76
	s_waitcnt lgkmcnt(0)
	v_cndmask_b32_e32 v71, v67, v69, vcc
	v_cndmask_b32_e32 v70, v66, v68, vcc
	v_cndmask_b32_e32 v69, v69, v67, vcc
	v_cndmask_b32_e32 v68, v68, v66, vcc
	v_lshl_add_u64 v[66:67], v[64:65], 0, v[176:177]
	global_store_dwordx4 v[66:67], v[68:71], off
	v_lshrrev_b32_e32 v67, 1, v72
	v_xor_b32_e32 v67, v67, v74
	v_lshlrev_b32_e32 v67, 4, v67
	v_lshlrev_b32_e32 v66, 7, v72
	v_and_b32_e32 v67, 0x70, v67
	v_or3_b32 v66, v75, v66, v67
	ds_read_b128 v[66:69], v66
	v_lshlrev_b32_e32 v176, 13, v72
	v_lshl_add_u64 v[64:65], v[64:65], 0, v[176:177]
	s_waitcnt lgkmcnt(0)
	v_cndmask_b32_e32 v71, v67, v69, vcc
	v_cndmask_b32_e32 v70, v66, v68, vcc
	v_cndmask_b32_e32 v69, v69, v67, vcc
	v_cndmask_b32_e32 v68, v68, v66, vcc
	global_store_dwordx4 v[64:65], v[68:71], off
	v_mov_b32_e32 v65, v192
	v_or_b32_e32 v64, 64, v120
	v_and_b32_e32 v68, 64, v65
	v_lshrrev_b32_e32 v65, 2, v65
	v_and_b32_e32 v65, 12, v65
	v_or3_b32 v66, s10, v65, v68
	v_ashrrev_i32_e32 v67, 31, v66
	v_lshl_add_u64 v[66:67], v[66:67], 2, s[0:1]
	global_load_dwordx4 v[70:73], v[66:67], off
	v_ashrrev_i32_e32 v65, 31, v64
	v_lshlrev_b32_e32 v176, 1, v68
	s_waitcnt vmcnt(0)
	v_pk_add_f32 v[62:63], v[62:63], v[72:73]
	v_pk_add_f32 v[60:61], v[60:61], v[70:71]
	v_pk_add_f32 v[58:59], v[58:59], v[72:73]
	v_pk_add_f32 v[56:57], v[56:57], v[70:71]
	v_pk_add_f32 v[54:55], v[54:55], v[72:73]
	v_pk_add_f32 v[52:53], v[52:53], v[70:71]
	v_pk_add_f32 v[50:51], v[50:51], v[72:73]
	v_pk_add_f32 v[48:49], v[48:49], v[70:71]
	global_load_dwordx4 v[70:73], v[66:67], off offset:64
	v_max_f32_e32 v60, 0, v60
	v_max_f32_e32 v61, 0, v61
	v_max_f32_e32 v56, 0, v56
	v_max_f32_e32 v57, 0, v57
	v_mul_f32_e32 v60, v60, v60
	v_mul_f32_e32 v61, v61, v61
	v_max_f32_e32 v62, 0, v62
	v_max_f32_e32 v63, 0, v63
	v_mul_f32_e32 v56, v56, v56
	v_mul_f32_e32 v57, v57, v57
	v_max_f32_e32 v58, 0, v58
	v_max_f32_e32 v59, 0, v59
	v_max_f32_e32 v52, 0, v52
	v_max_f32_e32 v53, 0, v53
	v_max_f32_e32 v48, 0, v48
	v_max_f32_e32 v49, 0, v49
	v_mul_f32_e32 v62, v62, v62
	v_mul_f32_e32 v63, v63, v63
	s_nop 1
	v_cvt_pk_bf16_f32 v60, v60, v61
	s_nop 1
	v_cvt_pk_bf16_f32 v61, v62, v63
	v_mul_f32_e32 v58, v58, v58
	v_mul_f32_e32 v59, v59, v59
	s_nop 1
	v_cvt_pk_bf16_f32 v56, v56, v57
	s_nop 1
	v_cvt_pk_bf16_f32 v57, v58, v59
	v_mul_f32_e32 v52, v52, v52
	v_mul_f32_e32 v53, v53, v53
	v_max_f32_e32 v54, 0, v54
	v_max_f32_e32 v55, 0, v55
	v_mul_f32_e32 v48, v48, v48
	v_mul_f32_e32 v49, v49, v49
	v_max_f32_e32 v50, 0, v50
	v_max_f32_e32 v51, 0, v51
	v_mul_f32_e32 v54, v54, v54
	v_mul_f32_e32 v55, v55, v55
	s_nop 1
	v_cvt_pk_bf16_f32 v52, v52, v53
	s_nop 1
	v_cvt_pk_bf16_f32 v53, v54, v55
	v_mul_f32_e32 v50, v50, v50
	v_mul_f32_e32 v51, v51, v51
	s_nop 1
	v_cvt_pk_bf16_f32 v48, v48, v49
	s_nop 1
	v_cvt_pk_bf16_f32 v49, v50, v51
	s_waitcnt vmcnt(0)
	v_pk_add_f32 v[46:47], v[46:47], v[72:73]
	v_pk_add_f32 v[44:45], v[44:45], v[70:71]
	v_pk_add_f32 v[42:43], v[42:43], v[72:73]
	v_pk_add_f32 v[40:41], v[40:41], v[70:71]
	v_pk_add_f32 v[38:39], v[38:39], v[72:73]
	v_pk_add_f32 v[36:37], v[36:37], v[70:71]
	v_pk_add_f32 v[34:35], v[34:35], v[72:73]
	v_pk_add_f32 v[32:33], v[32:33], v[70:71]
	global_load_dwordx4 v[70:73], v[66:67], off offset:128
	v_max_f32_e32 v44, 0, v44
	v_max_f32_e32 v45, 0, v45
	v_max_f32_e32 v40, 0, v40
	v_max_f32_e32 v41, 0, v41
	v_max_f32_e32 v36, 0, v36
	v_max_f32_e32 v37, 0, v37
	v_max_f32_e32 v32, 0, v32
	v_max_f32_e32 v33, 0, v33
	v_mul_f32_e32 v44, v44, v44
	v_mul_f32_e32 v45, v45, v45
	v_max_f32_e32 v46, 0, v46
	v_max_f32_e32 v47, 0, v47
	v_mul_f32_e32 v40, v40, v40
	v_mul_f32_e32 v41, v41, v41
	v_max_f32_e32 v42, 0, v42
	v_max_f32_e32 v43, 0, v43
	v_mul_f32_e32 v36, v36, v36
	v_mul_f32_e32 v37, v37, v37
	v_max_f32_e32 v38, 0, v38
	v_max_f32_e32 v39, 0, v39
	v_mul_f32_e32 v32, v32, v32
	v_mul_f32_e32 v33, v33, v33
	v_max_f32_e32 v34, 0, v34
	v_max_f32_e32 v35, 0, v35
	v_mul_f32_e32 v46, v46, v46
	v_mul_f32_e32 v47, v47, v47
	s_nop 1
	v_cvt_pk_bf16_f32 v44, v44, v45
	s_nop 1
	v_cvt_pk_bf16_f32 v45, v46, v47
	v_mul_f32_e32 v42, v42, v42
	v_mul_f32_e32 v43, v43, v43
	s_nop 1
	v_cvt_pk_bf16_f32 v40, v40, v41
	s_nop 1
	v_cvt_pk_bf16_f32 v41, v42, v43
	v_mul_f32_e32 v38, v38, v38
	v_mul_f32_e32 v39, v39, v39
	s_nop 1
	v_cvt_pk_bf16_f32 v36, v36, v37
	s_nop 1
	v_cvt_pk_bf16_f32 v37, v38, v39
	v_mul_f32_e32 v34, v34, v34
	v_mul_f32_e32 v35, v35, v35
	s_nop 1
	v_cvt_pk_bf16_f32 v32, v32, v33
	s_nop 1
	v_cvt_pk_bf16_f32 v33, v34, v35
	s_waitcnt vmcnt(0)
	v_pk_add_f32 v[22:23], v[22:23], v[72:73]
	v_pk_add_f32 v[20:21], v[20:21], v[70:71]
	v_pk_add_f32 v[18:19], v[18:19], v[72:73]
	v_pk_add_f32 v[16:17], v[16:17], v[70:71]
	v_max_f32_e32 v20, 0, v20
	v_max_f32_e32 v21, 0, v21
	v_max_f32_e32 v22, 0, v22
	v_max_f32_e32 v23, 0, v23
	v_max_f32_e32 v16, 0, v16
	v_max_f32_e32 v17, 0, v17
	v_max_f32_e32 v18, 0, v18
	v_max_f32_e32 v19, 0, v19
	v_mul_f32_e32 v20, v20, v20
	v_mul_f32_e32 v21, v21, v21
	v_mul_f32_e32 v22, v22, v22
	v_mul_f32_e32 v23, v23, v23
	v_mul_f32_e32 v16, v16, v16
	v_mul_f32_e32 v17, v17, v17
	v_mul_f32_e32 v18, v18, v18
	v_mul_f32_e32 v19, v19, v19
	s_nop 1
	v_cvt_pk_bf16_f32 v20, v20, v21
	s_nop 1
	v_cvt_pk_bf16_f32 v21, v22, v23
	s_nop 1
	v_cvt_pk_bf16_f32 v22, v16, v17
	s_nop 1
	v_cvt_pk_bf16_f32 v23, v18, v19
	global_load_dwordx4 v[16:19], v[66:67], off offset:192
	v_pk_add_f32 v[28:29], v[28:29], v[70:71]
	v_pk_add_f32 v[24:25], v[24:25], v[70:71]
	v_pk_add_f32 v[30:31], v[30:31], v[72:73]
	v_max_f32_e32 v28, 0, v28
	v_max_f32_e32 v29, 0, v29
	v_pk_add_f32 v[26:27], v[26:27], v[72:73]
	v_max_f32_e32 v24, 0, v24
	v_max_f32_e32 v25, 0, v25
	v_mul_f32_e32 v28, v28, v28
	v_mul_f32_e32 v29, v29, v29
	v_max_f32_e32 v30, 0, v30
	v_max_f32_e32 v31, 0, v31
	v_mul_f32_e32 v24, v24, v24
	v_mul_f32_e32 v25, v25, v25
	v_max_f32_e32 v26, 0, v26
	v_max_f32_e32 v27, 0, v27
	v_mul_f32_e32 v30, v30, v30
	v_mul_f32_e32 v31, v31, v31
	s_nop 1
	v_cvt_pk_bf16_f32 v28, v28, v29
	s_nop 1
	v_cvt_pk_bf16_f32 v29, v30, v31
	v_mul_f32_e32 v26, v26, v26
	v_mul_f32_e32 v27, v27, v27
	s_nop 1
	v_cvt_pk_bf16_f32 v24, v24, v25
	s_nop 1
	v_cvt_pk_bf16_f32 v25, v26, v27
	s_waitcnt vmcnt(0)
	v_pk_add_f32 v[2:3], v[2:3], v[18:19]
	v_pk_add_f32 v[0:1], v[0:1], v[16:17]
	v_max_f32_e32 v2, 0, v2
	v_max_f32_e32 v0, 0, v0
	v_max_f32_e32 v1, 0, v1
	v_max_f32_e32 v3, 0, v3
	v_pk_add_f32 v[10:11], v[10:11], v[18:19]
	v_pk_add_f32 v[8:9], v[8:9], v[16:17]
	v_mul_f32_e32 v0, v0, v0
	v_mul_f32_e32 v1, v1, v1
	v_mul_f32_e32 v2, v2, v2
	v_mul_f32_e32 v3, v3, v3
	v_max_f32_e32 v8, 0, v8
	v_max_f32_e32 v9, 0, v9
	v_max_f32_e32 v10, 0, v10
	s_nop 1
	v_cvt_pk_bf16_f32 v0, v0, v1
	s_nop 1
	v_cvt_pk_bf16_f32 v1, v2, v3
	v_pk_add_f32 v[2:3], v[14:15], v[18:19]
	v_mul_f32_e32 v8, v8, v8
	v_mul_f32_e32 v9, v9, v9
	v_mul_f32_e32 v10, v10, v10
	v_max_f32_e32 v11, 0, v11
	v_max_f32_e32 v2, 0, v2
	v_mul_f32_e32 v11, v11, v11
	s_nop 1
	v_cvt_pk_bf16_f32 v8, v8, v9
	s_nop 1
	v_cvt_pk_bf16_f32 v9, v10, v11
	v_pk_add_f32 v[6:7], v[6:7], v[18:19]
	v_pk_add_f32 v[4:5], v[4:5], v[16:17]
	v_mul_f32_e32 v10, v2, v2
	v_max_f32_e32 v2, 0, v3
	v_max_f32_e32 v4, 0, v4
	v_max_f32_e32 v5, 0, v5
	v_max_f32_e32 v6, 0, v6
	v_max_f32_e32 v7, 0, v7
	v_mul_f32_e32 v3, v2, v2
	v_mul_f32_e32 v4, v4, v4
	v_mul_f32_e32 v5, v5, v5
	v_mul_f32_e32 v6, v6, v6
	v_mul_f32_e32 v7, v7, v7
	s_nop 1
	v_cvt_pk_bf16_f32 v3, v10, v3
	v_mov_b32_e32 v10, v192
	s_nop 1
	v_cvt_pk_bf16_f32 v4, v4, v5
	s_nop 1
	v_cvt_pk_bf16_f32 v5, v6, v7
	v_pk_add_f32 v[6:7], v[12:13], v[16:17]
	s_nop 0
	v_lshlrev_b32_e32 v13, 7, v10
	v_max_f32_e32 v6, 0, v6
	v_max_f32_e32 v7, 0, v7
	v_and_b32_e32 v11, 15, v10
	v_bfe_u32 v12, v10, 4, 2
	v_and_b32_e32 v13, 0xffffe000, v13
	v_mul_f32_e32 v6, v6, v6
	v_mul_f32_e32 v7, v7, v7
	v_lshl_or_b32 v14, v11, 7, v13
	v_bitop3_b32 v15, v12, v10, 15 bitop3:0x78
	s_nop 1
	v_cvt_pk_bf16_f32 v2, v6, v7
	v_lshlrev_b64 v[6:7], 13, v[64:65]
	v_lshl_or_b32 v15, v15, 3, v14
	v_bitop3_b32 v16, v12, v11, 4 bitop3:0x36
	v_bitop3_b32 v17, v12, v11, 8 bitop3:0x36
	v_bitop3_b32 v11, v12, v11, 12 bitop3:0x36
	v_lshl_add_u64 v[6:7], s[4:5], 0, v[6:7]
	v_lshl_or_b32 v16, v16, 3, v14
	v_lshl_or_b32 v17, v17, 3, v14
	v_lshl_or_b32 v11, v11, 3, v14
	ds_write2st64_b64 v15, v[60:61], v[56:57] offset1:4
	ds_write2st64_b64 v16, v[44:45], v[40:41] offset1:4
	ds_write2st64_b64 v17, v[28:29], v[24:25] offset1:4
	ds_write2st64_b64 v11, v[8:9], v[4:5] offset1:4
	ds_write2st64_b64 v15, v[52:53], v[48:49] offset0:8 offset1:12
	ds_write2st64_b64 v16, v[36:37], v[32:33] offset0:8 offset1:12
	ds_write2st64_b64 v17, v[20:21], v[22:23] offset0:8 offset1:12
	ds_write2st64_b64 v11, v[0:1], v[2:3] offset0:8 offset1:12
	v_bfe_u32 v8, v10, 3, 3
	v_lshlrev_b32_e32 v2, 4, v10
	v_and_b32_e32 v4, 48, v10
	v_lshl_add_u64 v[6:7], v[6:7], 0, s[12:13]
	v_lshlrev_b32_e32 v3, 7, v8
	v_bitop3_b32 v9, v2, v4, s11 bitop3:0x6c
	v_lshl_add_u64 v[6:7], v[6:7], 0, v[176:177]
	v_and_b32_e32 v176, 0x70, v2
	v_or3_b32 v2, v13, v3, v9
	ds_read_b128 v[2:5], v2
	v_and_b32_e32 v0, 8, v10
	v_cmp_eq_u32_e32 vcc, 0, v0
	v_lshl_add_u64 v[0:1], v[6:7], 0, v[176:177]
	v_lshlrev_b32_e32 v176, 13, v8
	s_waitcnt lgkmcnt(0)
	v_cndmask_b32_e32 v7, v3, v5, vcc
	v_cndmask_b32_e32 v6, v2, v4, vcc
	v_cndmask_b32_e32 v5, v5, v3, vcc
	v_cndmask_b32_e32 v4, v4, v2, vcc
	v_lshl_add_u64 v[2:3], v[0:1], 0, v[176:177]
	v_or_b32_e32 v11, 8, v8
	global_store_dwordx4 v[2:3], v[4:7], off
	v_lshrrev_b32_e32 v3, 1, v11
	v_xor_b32_e32 v3, v3, v10
	v_lshlrev_b32_e32 v3, 4, v3
	v_lshlrev_b32_e32 v2, 7, v11
	v_and_b32_e32 v3, 0x70, v3
	v_or3_b32 v2, v13, v2, v3
	ds_read_b128 v[2:5], v2
	v_lshlrev_b32_e32 v176, 13, v11
	v_or_b32_e32 v11, 16, v8
	s_waitcnt lgkmcnt(0)
	v_cndmask_b32_e32 v7, v3, v5, vcc
	v_cndmask_b32_e32 v6, v2, v4, vcc
	v_cndmask_b32_e32 v5, v5, v3, vcc
	v_cndmask_b32_e32 v4, v4, v2, vcc
	v_lshl_add_u64 v[2:3], v[0:1], 0, v[176:177]
	global_store_dwordx4 v[2:3], v[4:7], off
	v_lshlrev_b32_e32 v2, 7, v11
	v_or3_b32 v2, v13, v2, v9
	ds_read_b128 v[2:5], v2
	v_lshlrev_b32_e32 v176, 13, v11
	v_or_b32_e32 v11, 24, v8
	s_waitcnt lgkmcnt(0)
	v_cndmask_b32_e32 v7, v3, v5, vcc
	v_cndmask_b32_e32 v6, v2, v4, vcc
	v_cndmask_b32_e32 v5, v5, v3, vcc
	v_cndmask_b32_e32 v4, v4, v2, vcc
	v_lshl_add_u64 v[2:3], v[0:1], 0, v[176:177]
	global_store_dwordx4 v[2:3], v[4:7], off
	v_lshrrev_b32_e32 v3, 1, v11
	v_xor_b32_e32 v3, v3, v10
	v_lshlrev_b32_e32 v3, 4, v3
	v_lshlrev_b32_e32 v2, 7, v11
	v_and_b32_e32 v3, 0x70, v3
	v_or3_b32 v2, v13, v2, v3
	ds_read_b128 v[2:5], v2
	v_lshlrev_b32_e32 v176, 13, v11
	v_or_b32_e32 v11, 32, v8
	s_waitcnt lgkmcnt(0)
	v_cndmask_b32_e32 v7, v3, v5, vcc
	v_cndmask_b32_e32 v6, v2, v4, vcc
	v_cndmask_b32_e32 v5, v5, v3, vcc
	v_cndmask_b32_e32 v4, v4, v2, vcc
	v_lshl_add_u64 v[2:3], v[0:1], 0, v[176:177]
	global_store_dwordx4 v[2:3], v[4:7], off
	v_lshlrev_b32_e32 v2, 7, v11
	v_or3_b32 v2, v13, v2, v9
	ds_read_b128 v[2:5], v2
	v_lshlrev_b32_e32 v176, 13, v11
	v_or_b32_e32 v11, 40, v8
	s_waitcnt lgkmcnt(0)
	v_cndmask_b32_e32 v7, v3, v5, vcc
	v_cndmask_b32_e32 v6, v2, v4, vcc
	v_cndmask_b32_e32 v5, v5, v3, vcc
	v_cndmask_b32_e32 v4, v4, v2, vcc
	v_lshl_add_u64 v[2:3], v[0:1], 0, v[176:177]
	global_store_dwordx4 v[2:3], v[4:7], off
	v_lshrrev_b32_e32 v3, 1, v11
	v_xor_b32_e32 v3, v3, v10
	v_lshlrev_b32_e32 v3, 4, v3
	v_lshlrev_b32_e32 v2, 7, v11
	v_and_b32_e32 v3, 0x70, v3
	v_or3_b32 v2, v13, v2, v3
	ds_read_b128 v[2:5], v2
	v_lshlrev_b32_e32 v176, 13, v11
	v_or_b32_e32 v11, 48, v8
	v_or_b32_e32 v8, 56, v8
	s_waitcnt lgkmcnt(0)
	v_cndmask_b32_e32 v7, v3, v5, vcc
	v_cndmask_b32_e32 v6, v2, v4, vcc
	v_cndmask_b32_e32 v5, v5, v3, vcc
	v_cndmask_b32_e32 v4, v4, v2, vcc
	v_lshl_add_u64 v[2:3], v[0:1], 0, v[176:177]
	global_store_dwordx4 v[2:3], v[4:7], off
	v_lshlrev_b32_e32 v2, 7, v11
	v_or3_b32 v2, v13, v2, v9
	ds_read_b128 v[2:5], v2
	v_lshlrev_b32_e32 v176, 13, v11
	s_waitcnt lgkmcnt(0)
	v_cndmask_b32_e32 v7, v3, v5, vcc
	v_cndmask_b32_e32 v6, v2, v4, vcc
	v_cndmask_b32_e32 v5, v5, v3, vcc
	v_cndmask_b32_e32 v4, v4, v2, vcc
	v_lshl_add_u64 v[2:3], v[0:1], 0, v[176:177]
	global_store_dwordx4 v[2:3], v[4:7], off
	v_lshrrev_b32_e32 v3, 1, v8
	v_xor_b32_e32 v3, v3, v10
	v_lshlrev_b32_e32 v3, 4, v3
	v_lshlrev_b32_e32 v2, 7, v8
	v_and_b32_e32 v3, 0x70, v3
	v_or3_b32 v2, v13, v2, v3
	ds_read_b128 v[2:5], v2
	v_lshlrev_b32_e32 v176, 13, v8
	v_lshl_add_u64 v[0:1], v[0:1], 0, v[176:177]
	s_waitcnt lgkmcnt(0)
	v_cndmask_b32_e32 v7, v3, v5, vcc
	v_cndmask_b32_e32 v6, v2, v4, vcc
	v_cndmask_b32_e32 v5, v5, v3, vcc
	v_cndmask_b32_e32 v4, v4, v2, vcc
	global_store_dwordx4 v[0:1], v[4:7], off
	s_cbranch_scc0 .LBB0_174

.LBB0_634:
	s_waitcnt vmcnt(5)
	ds_write_b128 v187, v[128:131]
	ds_write_b128 v187, v[136:139] offset:4096
	ds_write_b128 v187, v[140:143] offset:8192
	ds_write_b128 v187, v[144:147] offset:12288
	ds_write_b128 v187, v[148:151] offset:16384
	ds_write_b128 v187, v[152:155] offset:20480
	s_waitcnt vmcnt(4)
	ds_write_b128 v187, v[156:159] offset:24576
	s_waitcnt vmcnt(3)
	ds_write_b128 v187, v[160:163] offset:28672
	ds_write_b128 v187, v[132:135] offset:32768
	s_waitcnt vmcnt(2)
	ds_write_b128 v187, v[164:167] offset:36864
	s_waitcnt vmcnt(1)
	ds_write_b128 v187, v[168:171] offset:40960
	s_waitcnt vmcnt(0)
	ds_write_b128 v187, v[172:175] offset:45056
	v_add_u32_e32 v148, v176, v184
	s_waitcnt lgkmcnt(0)
	s_barrier
	v_add_u32_e32 v152, v176, v185
	ds_read_b128 v[128:131], v148 offset:32768
	ds_read_b128 v[132:135], v148 offset:34816
	ds_read_b128 v[136:139], v152
	ds_read_b128 v[140:143], v152 offset:2048
	ds_read_b128 v[144:147], v148 offset:36864
	ds_read_b128 v[148:151], v148 offset:38912
	ds_read_b128 v[230:233], v152 offset:4096
	ds_read_b128 v[234:237], v152 offset:6144
	ds_read_b128 v[238:241], v152 offset:8192
	ds_read_b128 v[242:245], v152 offset:10240
	s_waitcnt lgkmcnt(7)
	v_mfma_f32_16x16x32_bf16 v[124:127], v[128:131], v[136:139], v[124:127]
	v_add_u32_e32 v156, v186, v185
	s_min_i32 s4, s1, 15
	s_lshl_b32 s56, s4, 7
	v_mfma_f32_16x16x32_bf16 v[120:123], v[132:135], v[136:139], v[120:123]
	s_add_i32 s1, s1, 1
	s_cmp_lg_u32 s1, 17
	s_waitcnt lgkmcnt(5)
	v_mfma_f32_16x16x32_bf16 v[116:119], v[144:147], v[136:139], v[116:119]
	s_waitcnt lgkmcnt(4)
	v_mfma_f32_16x16x32_bf16 v[112:115], v[148:151], v[136:139], v[112:115]
	v_mfma_f32_16x16x32_bf16 v[108:111], v[128:131], v[140:143], v[108:111]
	v_mfma_f32_16x16x32_bf16 v[104:107], v[132:135], v[140:143], v[104:107]
	v_mfma_f32_16x16x32_bf16 v[100:103], v[144:147], v[140:143], v[100:103]
	v_mfma_f32_16x16x32_bf16 v[96:99], v[148:151], v[140:143], v[96:99]
	ds_read_b128 v[136:139], v152 offset:12288
	ds_read_b128 v[140:143], v152 offset:14336
	s_waitcnt lgkmcnt(5)
	v_mfma_f32_16x16x32_bf16 v[92:95], v[128:131], v[230:233], v[92:95]
	v_mfma_f32_16x16x32_bf16 v[88:91], v[132:135], v[230:233], v[88:91]
	v_mfma_f32_16x16x32_bf16 v[84:87], v[144:147], v[230:233], v[84:87]
	v_mfma_f32_16x16x32_bf16 v[80:83], v[148:151], v[230:233], v[80:83]
	s_waitcnt lgkmcnt(4)
	v_mfma_f32_16x16x32_bf16 v[76:79], v[128:131], v[234:237], v[76:79]
	v_mfma_f32_16x16x32_bf16 v[72:75], v[132:135], v[234:237], v[72:75]
	v_mfma_f32_16x16x32_bf16 v[68:71], v[144:147], v[234:237], v[68:71]
	v_mfma_f32_16x16x32_bf16 v[64:67], v[148:151], v[234:237], v[64:67]
	s_waitcnt lgkmcnt(3)
	v_mfma_f32_16x16x32_bf16 v[60:63], v[128:131], v[238:241], v[60:63]
	v_mfma_f32_16x16x32_bf16 v[56:59], v[132:135], v[238:241], v[56:59]
	v_mfma_f32_16x16x32_bf16 v[52:55], v[144:147], v[238:241], v[52:55]
	v_mfma_f32_16x16x32_bf16 v[48:51], v[148:151], v[238:241], v[48:51]
	s_waitcnt lgkmcnt(2)
	v_mfma_f32_16x16x32_bf16 v[44:47], v[128:131], v[242:245], v[44:47]
	v_mfma_f32_16x16x32_bf16 v[40:43], v[132:135], v[242:245], v[40:43]
	v_mfma_f32_16x16x32_bf16 v[36:39], v[144:147], v[242:245], v[36:39]
	v_mfma_f32_16x16x32_bf16 v[32:35], v[148:151], v[242:245], v[32:35]
	s_waitcnt lgkmcnt(1)
	v_mfma_f32_16x16x32_bf16 v[28:31], v[128:131], v[136:139], v[28:31]
	v_mfma_f32_16x16x32_bf16 v[24:27], v[132:135], v[136:139], v[24:27]
	v_mfma_f32_16x16x32_bf16 v[20:23], v[144:147], v[136:139], v[20:23]
	v_mfma_f32_16x16x32_bf16 v[16:19], v[148:151], v[136:139], v[16:19]
	v_add_u32_e32 v136, v186, v184
	ds_read_b128 v[152:155], v136 offset:32768
	ds_read_b128 v[160:163], v136 offset:34816
	s_waitcnt lgkmcnt(2)
	v_mfma_f32_16x16x32_bf16 v[12:15], v[128:131], v[140:143], v[12:15]
	v_mfma_f32_16x16x32_bf16 v[4:7], v[132:135], v[140:143], v[4:7]
	ds_read_b128 v[128:131], v156
	ds_read_b128 v[132:135], v156 offset:2048
	ds_read_b128 v[172:175], v136 offset:36864
	ds_read_b128 v[188:191], v136 offset:38912
	ds_read_b128 v[230:233], v156 offset:4096
	ds_read_b128 v[234:237], v156 offset:6144
	s_waitcnt lgkmcnt(5)
	v_mfma_f32_16x16x32_bf16 v[124:127], v[152:155], v[128:131], v[124:127]
	v_mfma_f32_16x16x32_bf16 v[120:123], v[160:163], v[128:131], v[120:123]
	s_waitcnt lgkmcnt(3)
	v_mfma_f32_16x16x32_bf16 v[116:119], v[172:175], v[128:131], v[116:119]
	s_waitcnt lgkmcnt(2)
	v_mfma_f32_16x16x32_bf16 v[112:115], v[188:191], v[128:131], v[112:115]
	v_mfma_f32_16x16x32_bf16 v[108:111], v[152:155], v[132:135], v[108:111]
	v_mfma_f32_16x16x32_bf16 v[104:107], v[160:163], v[132:135], v[104:107]
	v_mfma_f32_16x16x32_bf16 v[100:103], v[172:175], v[132:135], v[100:103]
	v_mfma_f32_16x16x32_bf16 v[96:99], v[188:191], v[132:135], v[96:99]
	s_waitcnt lgkmcnt(0)
	v_mfma_f32_16x16x32_bf16 v[76:79], v[152:155], v[234:237], v[76:79]
	v_mfma_f32_16x16x32_bf16 v[72:75], v[160:163], v[234:237], v[72:75]
	v_mfma_f32_16x16x32_bf16 v[68:71], v[172:175], v[234:237], v[68:71]
	v_mfma_f32_16x16x32_bf16 v[64:67], v[188:191], v[234:237], v[64:67]
	v_lshl_add_u64 v[132:133], v[178:179], 0, s[56:57]
	v_mfma_f32_16x16x32_bf16 v[8:11], v[148:151], v[140:143], v[8:11]
	v_add_co_u32_e32 v150, vcc, s65, v132
	v_lshl_add_u64 v[148:149], v[180:181], 0, s[56:57]
	s_nop 0
	v_addc_co_u32_e32 v151, vcc, 0, v133, vcc
	v_mfma_f32_16x16x32_bf16 v[0:3], v[144:147], v[140:143], v[0:3]
	ds_read_b128 v[136:139], v156 offset:8192
	ds_read_b128 v[140:143], v156 offset:10240
	ds_read_b128 v[144:147], v156 offset:12288
	ds_read_b128 v[220:223], v156 offset:14336
	v_add_co_u32_e32 v156, vcc, s46, v132
	v_mfma_f32_16x16x32_bf16 v[92:95], v[152:155], v[230:233], v[92:95]
	s_nop 0
	v_addc_co_u32_e32 v157, vcc, 0, v133, vcc
	v_add_co_u32_e32 v158, vcc, s47, v132
	v_mfma_f32_16x16x32_bf16 v[88:91], v[160:163], v[230:233], v[88:91]
	s_nop 0
	v_addc_co_u32_e32 v159, vcc, 0, v133, vcc
	v_add_co_u32_e32 v164, vcc, s33, v132
	v_mfma_f32_16x16x32_bf16 v[84:87], v[172:175], v[230:233], v[84:87]
	s_nop 0
	v_addc_co_u32_e32 v165, vcc, 0, v133, vcc
	v_add_co_u32_e32 v166, vcc, s44, v132
	v_mfma_f32_16x16x32_bf16 v[80:83], v[188:191], v[230:233], v[80:83]
	s_nop 0
	v_addc_co_u32_e32 v167, vcc, 0, v133, vcc
	v_add_co_u32_e32 v168, vcc, s48, v132
	s_waitcnt lgkmcnt(3)
	v_mfma_f32_16x16x32_bf16 v[60:63], v[152:155], v[136:139], v[60:63]
	v_addc_co_u32_e32 v169, vcc, 0, v133, vcc
	v_add_co_u32_e32 v170, vcc, s45, v132
	global_load_dwordx4 v[128:131], v[132:133], off
	s_nop 0
	v_addc_co_u32_e32 v171, vcc, 0, v133, vcc
	v_add_co_u32_e32 v224, vcc, s65, v148
	v_mfma_f32_16x16x32_bf16 v[56:59], v[160:163], v[136:139], v[56:59]
	s_nop 0
	v_addc_co_u32_e32 v225, vcc, 0, v149, vcc
	v_add_co_u32_e32 v226, vcc, s46, v148
	v_mfma_f32_16x16x32_bf16 v[52:55], v[172:175], v[136:139], v[52:55]
	s_nop 0
	v_addc_co_u32_e32 v227, vcc, 0, v149, vcc
	v_add_co_u32_e32 v228, vcc, s47, v148
	v_mfma_f32_16x16x32_bf16 v[48:51], v[188:191], v[136:139], v[48:51]
	global_load_dwordx4 v[132:135], v[148:149], off
	v_addc_co_u32_e32 v229, vcc, 0, v149, vcc
	s_waitcnt lgkmcnt(2)
	v_mfma_f32_16x16x32_bf16 v[44:47], v[152:155], v[140:143], v[44:47]
	v_mfma_f32_16x16x32_bf16 v[40:43], v[160:163], v[140:143], v[40:43]
	v_mfma_f32_16x16x32_bf16 v[36:39], v[172:175], v[140:143], v[36:39]
	v_mfma_f32_16x16x32_bf16 v[32:35], v[188:191], v[140:143], v[32:35]
	s_waitcnt lgkmcnt(1)
	v_mfma_f32_16x16x32_bf16 v[28:31], v[152:155], v[144:147], v[28:31]
	v_mfma_f32_16x16x32_bf16 v[24:27], v[160:163], v[144:147], v[24:27]
	v_mfma_f32_16x16x32_bf16 v[20:23], v[172:175], v[144:147], v[20:23]
	v_mfma_f32_16x16x32_bf16 v[16:19], v[188:191], v[144:147], v[16:19]
	global_load_dwordx4 v[136:139], v[150:151], off
	global_load_dwordx4 v[140:143], v[156:157], off
	global_load_dwordx4 v[144:147], v[158:159], off
	s_waitcnt lgkmcnt(0)
	v_mfma_f32_16x16x32_bf16 v[12:15], v[152:155], v[220:223], v[12:15]
	global_load_dwordx4 v[148:151], v[164:165], off
	global_load_dwordx4 v[152:155], v[166:167], off
	global_load_dwordx4 v[156:159], v[168:169], off
	v_mfma_f32_16x16x32_bf16 v[4:7], v[160:163], v[220:223], v[4:7]
	global_load_dwordx4 v[160:163], v[170:171], off
	global_load_dwordx4 v[164:167], v[224:225], off
	s_nop 0
	global_load_dwordx4 v[168:171], v[226:227], off
	v_mfma_f32_16x16x32_bf16 v[0:3], v[172:175], v[220:223], v[0:3]
	global_load_dwordx4 v[172:175], v[228:229], off
	s_barrier
	v_mfma_f32_16x16x32_bf16 v[8:11], v[188:191], v[220:223], v[8:11]
	s_cbranch_scc1 .LBB0_634
	s_cmp_lt_i32 s20, 16
	s_waitcnt vmcnt(11)
	v_mov_b32_e32 v129, v192
	s_cselect_b64 s[24:25], -1, 0
	s_cmp_gt_i32 s20, 15
	v_lshl_add_u32 v128, s0, 8, v183
	s_cselect_b64 s[22:23], -1, 0
	s_waitcnt vmcnt(9)
	v_bfe_u32 v136, v129, 6, 1
	s_and_b64 vcc, exec, s[24:25]
	s_mov_b64 s[0:1], s[24:25]
	s_cbranch_vccnz .LBB0_686
	s_sub_i32 s0, s20, 18
	s_cmp_gt_u32 s0, 3
	s_mov_b64 s[0:1], -1
	s_cbranch_scc0 .LBB0_686
	s_cmp_gt_u32 s20, 21
	s_cselect_b64 s[0:1], -1, 0
	s_cmp_gt_u32 s20, 17
	v_bfe_u32 v131, v129, 4, 2
	v_and_or_b32 v130, v129, 15, v128
	s_cselect_b64 s[26:27], -1, 0
	v_cndmask_b32_e64 v132, 0, 1, s[0:1]
	v_cmp_ne_u32_e64 s[40:41], 0, v136
	v_cmp_gt_u32_e64 s[38:39], 2, v131
	v_lshlrev_b32_e32 v129, 2, v131
	v_ashrrev_i32_e32 v131, 31, v130
	s_mov_b64 s[4:5], -1
	s_and_b64 vcc, exec, s[26:27]
	v_cmp_ne_u32_e64 s[0:1], 1, v132
	s_cbranch_vccz .LBB0_647
	s_and_b64 vcc, exec, s[0:1]
	s_cbranch_vccnz .LBB0_646
	s_and_saveexec_b64 s[4:5], s[40:41]
	s_xor_b64 s[4:5], exec, s[4:5]
	s_cbranch_execz .LBB0_643
	s_and_saveexec_b64 s[28:29], s[38:39]
	s_cbranch_execz .LBB0_642
	v_lshlrev_b64 v[132:133], 5, v[130:131]
	v_lshl_add_u64 v[132:133], s[10:11], 0, v[132:133]
	v_lshlrev_b32_e32 v176, 2, v129
	s_mov_b32 s44, 0x3d3504f3
	v_lshl_add_u64 v[138:139], v[132:133], 0, v[176:177]
	v_pk_mul_f32 v[134:135], v[126:127], s[44:45] op_sel_hi:[1,0]
	v_pk_mul_f32 v[132:133], v[124:125], s[44:45] op_sel_hi:[1,0]
	global_store_dwordx4 v[138:139], v[132:135], off

.LBB0_1353:
	s_waitcnt vmcnt(5)
	ds_write_b128 v187, v[128:131]
	ds_write_b128 v187, v[136:139] offset:4096
	ds_write_b128 v187, v[140:143] offset:8192
	ds_write_b128 v187, v[144:147] offset:12288
	ds_write_b128 v187, v[148:151] offset:16384
	ds_write_b128 v187, v[152:155] offset:20480
	s_waitcnt vmcnt(4)
	ds_write_b128 v187, v[156:159] offset:24576
	s_waitcnt vmcnt(3)
	ds_write_b128 v187, v[160:163] offset:28672
	ds_write_b128 v187, v[132:135] offset:32768
	s_waitcnt vmcnt(2)
	ds_write_b128 v187, v[164:167] offset:36864
	s_waitcnt vmcnt(1)
	ds_write_b128 v187, v[168:171] offset:40960
	s_waitcnt vmcnt(0)
	ds_write_b128 v187, v[172:175] offset:45056
	v_add_u32_e32 v148, v176, v184
	s_waitcnt lgkmcnt(0)
	s_barrier
	v_add_u32_e32 v152, v176, v185
	ds_read_b128 v[128:131], v148 offset:32768
	ds_read_b128 v[132:135], v148 offset:34816
	ds_read_b128 v[136:139], v152
	ds_read_b128 v[140:143], v152 offset:2048
	ds_read_b128 v[144:147], v148 offset:36864
	ds_read_b128 v[148:151], v148 offset:38912
	ds_read_b128 v[230:233], v152 offset:4096
	ds_read_b128 v[234:237], v152 offset:6144
	ds_read_b128 v[238:241], v152 offset:8192
	ds_read_b128 v[242:245], v152 offset:10240
	s_waitcnt lgkmcnt(7)
	v_mfma_f32_16x16x32_bf16 v[124:127], v[128:131], v[136:139], v[124:127]
	v_add_u32_e32 v156, v186, v185
	s_min_i32 s9, s1, 15
	s_lshl_b32 s56, s9, 7
	v_mfma_f32_16x16x32_bf16 v[120:123], v[132:135], v[136:139], v[120:123]
	s_add_i32 s1, s1, 1
	s_cmp_lg_u32 s1, 17
	s_waitcnt lgkmcnt(5)
	v_mfma_f32_16x16x32_bf16 v[116:119], v[144:147], v[136:139], v[116:119]
	s_waitcnt lgkmcnt(4)
	v_mfma_f32_16x16x32_bf16 v[112:115], v[148:151], v[136:139], v[112:115]
	v_mfma_f32_16x16x32_bf16 v[108:111], v[128:131], v[140:143], v[108:111]
	v_mfma_f32_16x16x32_bf16 v[104:107], v[132:135], v[140:143], v[104:107]
	v_mfma_f32_16x16x32_bf16 v[100:103], v[144:147], v[140:143], v[100:103]
	v_mfma_f32_16x16x32_bf16 v[96:99], v[148:151], v[140:143], v[96:99]
	ds_read_b128 v[136:139], v152 offset:12288
	ds_read_b128 v[140:143], v152 offset:14336
	s_waitcnt lgkmcnt(5)
	v_mfma_f32_16x16x32_bf16 v[92:95], v[128:131], v[230:233], v[92:95]
	v_mfma_f32_16x16x32_bf16 v[88:91], v[132:135], v[230:233], v[88:91]
	v_mfma_f32_16x16x32_bf16 v[84:87], v[144:147], v[230:233], v[84:87]
	v_mfma_f32_16x16x32_bf16 v[80:83], v[148:151], v[230:233], v[80:83]
	s_waitcnt lgkmcnt(4)
	v_mfma_f32_16x16x32_bf16 v[76:79], v[128:131], v[234:237], v[76:79]
	v_mfma_f32_16x16x32_bf16 v[72:75], v[132:135], v[234:237], v[72:75]
	v_mfma_f32_16x16x32_bf16 v[68:71], v[144:147], v[234:237], v[68:71]
	v_mfma_f32_16x16x32_bf16 v[64:67], v[148:151], v[234:237], v[64:67]
	s_waitcnt lgkmcnt(3)
	v_mfma_f32_16x16x32_bf16 v[60:63], v[128:131], v[238:241], v[60:63]
	v_mfma_f32_16x16x32_bf16 v[56:59], v[132:135], v[238:241], v[56:59]
	v_mfma_f32_16x16x32_bf16 v[52:55], v[144:147], v[238:241], v[52:55]
	v_mfma_f32_16x16x32_bf16 v[48:51], v[148:151], v[238:241], v[48:51]
	s_waitcnt lgkmcnt(2)
	v_mfma_f32_16x16x32_bf16 v[44:47], v[128:131], v[242:245], v[44:47]
	v_mfma_f32_16x16x32_bf16 v[40:43], v[132:135], v[242:245], v[40:43]
	v_mfma_f32_16x16x32_bf16 v[36:39], v[144:147], v[242:245], v[36:39]
	v_mfma_f32_16x16x32_bf16 v[32:35], v[148:151], v[242:245], v[32:35]
	s_waitcnt lgkmcnt(1)
	v_mfma_f32_16x16x32_bf16 v[28:31], v[128:131], v[136:139], v[28:31]
	v_mfma_f32_16x16x32_bf16 v[24:27], v[132:135], v[136:139], v[24:27]
	v_mfma_f32_16x16x32_bf16 v[20:23], v[144:147], v[136:139], v[20:23]
	v_mfma_f32_16x16x32_bf16 v[16:19], v[148:151], v[136:139], v[16:19]
	v_add_u32_e32 v136, v186, v184
	ds_read_b128 v[152:155], v136 offset:32768
	ds_read_b128 v[160:163], v136 offset:34816
	s_waitcnt lgkmcnt(2)
	v_mfma_f32_16x16x32_bf16 v[12:15], v[128:131], v[140:143], v[12:15]
	v_mfma_f32_16x16x32_bf16 v[8:11], v[132:135], v[140:143], v[8:11]
	ds_read_b128 v[128:131], v156
	ds_read_b128 v[132:135], v156 offset:2048
	ds_read_b128 v[172:175], v136 offset:36864
	ds_read_b128 v[188:191], v136 offset:38912
	ds_read_b128 v[230:233], v156 offset:4096
	ds_read_b128 v[234:237], v156 offset:6144
	s_waitcnt lgkmcnt(5)
	v_mfma_f32_16x16x32_bf16 v[124:127], v[152:155], v[128:131], v[124:127]
	v_mfma_f32_16x16x32_bf16 v[120:123], v[160:163], v[128:131], v[120:123]
	s_waitcnt lgkmcnt(3)
	v_mfma_f32_16x16x32_bf16 v[116:119], v[172:175], v[128:131], v[116:119]
	s_waitcnt lgkmcnt(2)
	v_mfma_f32_16x16x32_bf16 v[112:115], v[188:191], v[128:131], v[112:115]
	v_mfma_f32_16x16x32_bf16 v[108:111], v[152:155], v[132:135], v[108:111]
	v_mfma_f32_16x16x32_bf16 v[104:107], v[160:163], v[132:135], v[104:107]
	v_mfma_f32_16x16x32_bf16 v[100:103], v[172:175], v[132:135], v[100:103]
	v_mfma_f32_16x16x32_bf16 v[96:99], v[188:191], v[132:135], v[96:99]
	s_waitcnt lgkmcnt(0)
	v_mfma_f32_16x16x32_bf16 v[76:79], v[152:155], v[234:237], v[76:79]
	v_mfma_f32_16x16x32_bf16 v[72:75], v[160:163], v[234:237], v[72:75]
	v_mfma_f32_16x16x32_bf16 v[68:71], v[172:175], v[234:237], v[68:71]
	v_mfma_f32_16x16x32_bf16 v[64:67], v[188:191], v[234:237], v[64:67]
	v_lshl_add_u64 v[132:133], v[178:179], 0, s[56:57]
	v_mfma_f32_16x16x32_bf16 v[4:7], v[148:151], v[140:143], v[4:7]
	v_add_co_u32_e32 v150, vcc, s65, v132
	v_lshl_add_u64 v[148:149], v[180:181], 0, s[56:57]
	s_nop 0
	v_addc_co_u32_e32 v151, vcc, 0, v133, vcc
	v_mfma_f32_16x16x32_bf16 v[0:3], v[144:147], v[140:143], v[0:3]
	ds_read_b128 v[136:139], v156 offset:8192
	ds_read_b128 v[140:143], v156 offset:10240
	ds_read_b128 v[144:147], v156 offset:12288
	ds_read_b128 v[220:223], v156 offset:14336
	v_add_co_u32_e32 v156, vcc, s46, v132
	v_mfma_f32_16x16x32_bf16 v[92:95], v[152:155], v[230:233], v[92:95]
	s_nop 0
	v_addc_co_u32_e32 v157, vcc, 0, v133, vcc
	v_add_co_u32_e32 v158, vcc, s47, v132
	v_mfma_f32_16x16x32_bf16 v[88:91], v[160:163], v[230:233], v[88:91]
	s_nop 0
	v_addc_co_u32_e32 v159, vcc, 0, v133, vcc
	v_add_co_u32_e32 v164, vcc, s33, v132
	v_mfma_f32_16x16x32_bf16 v[84:87], v[172:175], v[230:233], v[84:87]
	s_nop 0
	v_addc_co_u32_e32 v165, vcc, 0, v133, vcc
	v_add_co_u32_e32 v166, vcc, s10, v132
	v_mfma_f32_16x16x32_bf16 v[80:83], v[188:191], v[230:233], v[80:83]
	s_nop 0
	v_addc_co_u32_e32 v167, vcc, 0, v133, vcc
	v_add_co_u32_e32 v168, vcc, s48, v132
	s_waitcnt lgkmcnt(3)
	v_mfma_f32_16x16x32_bf16 v[60:63], v[152:155], v[136:139], v[60:63]
	v_addc_co_u32_e32 v169, vcc, 0, v133, vcc
	v_add_co_u32_e32 v170, vcc, s11, v132
	global_load_dwordx4 v[128:131], v[132:133], off
	s_nop 0
	v_addc_co_u32_e32 v171, vcc, 0, v133, vcc
	v_add_co_u32_e32 v224, vcc, s65, v148
	v_mfma_f32_16x16x32_bf16 v[56:59], v[160:163], v[136:139], v[56:59]
	s_nop 0
	v_addc_co_u32_e32 v225, vcc, 0, v149, vcc
	v_add_co_u32_e32 v226, vcc, s46, v148
	v_mfma_f32_16x16x32_bf16 v[52:55], v[172:175], v[136:139], v[52:55]
	s_nop 0
	v_addc_co_u32_e32 v227, vcc, 0, v149, vcc
	v_add_co_u32_e32 v228, vcc, s47, v148
	v_mfma_f32_16x16x32_bf16 v[48:51], v[188:191], v[136:139], v[48:51]
	global_load_dwordx4 v[132:135], v[148:149], off
	v_addc_co_u32_e32 v229, vcc, 0, v149, vcc
	s_waitcnt lgkmcnt(2)
	v_mfma_f32_16x16x32_bf16 v[44:47], v[152:155], v[140:143], v[44:47]
	v_mfma_f32_16x16x32_bf16 v[40:43], v[160:163], v[140:143], v[40:43]
	v_mfma_f32_16x16x32_bf16 v[36:39], v[172:175], v[140:143], v[36:39]
	v_mfma_f32_16x16x32_bf16 v[32:35], v[188:191], v[140:143], v[32:35]
	s_waitcnt lgkmcnt(1)
	v_mfma_f32_16x16x32_bf16 v[28:31], v[152:155], v[144:147], v[28:31]
	v_mfma_f32_16x16x32_bf16 v[24:27], v[160:163], v[144:147], v[24:27]
	v_mfma_f32_16x16x32_bf16 v[20:23], v[172:175], v[144:147], v[20:23]
	v_mfma_f32_16x16x32_bf16 v[16:19], v[188:191], v[144:147], v[16:19]
	global_load_dwordx4 v[136:139], v[150:151], off
	global_load_dwordx4 v[140:143], v[156:157], off
	global_load_dwordx4 v[144:147], v[158:159], off
	s_waitcnt lgkmcnt(0)
	v_mfma_f32_16x16x32_bf16 v[12:15], v[152:155], v[220:223], v[12:15]
	global_load_dwordx4 v[148:151], v[164:165], off
	global_load_dwordx4 v[152:155], v[166:167], off
	global_load_dwordx4 v[156:159], v[168:169], off
	v_mfma_f32_16x16x32_bf16 v[8:11], v[160:163], v[220:223], v[8:11]
	global_load_dwordx4 v[160:163], v[170:171], off
	global_load_dwordx4 v[164:167], v[224:225], off
	s_nop 0
	global_load_dwordx4 v[168:171], v[226:227], off
	v_mfma_f32_16x16x32_bf16 v[0:3], v[172:175], v[220:223], v[0:3]
	global_load_dwordx4 v[172:175], v[228:229], off
	s_barrier
	v_mfma_f32_16x16x32_bf16 v[4:7], v[188:191], v[220:223], v[4:7]
	s_cbranch_scc1 .LBB0_1353
	s_cmp_gt_i32 s0, 9
	s_waitcnt vmcnt(11)
	v_mov_b32_e32 v128, v192
	s_cselect_b64 s[10:11], -1, 0
	s_cmp_lt_i32 s0, 10
	s_cbranch_scc1 .LBB0_1356
	v_mul_f32_e32 v129, 0x3d372713, v124
	v_mul_f32_e32 v129, v124, v129
	v_fma_f32 v129, v124, v129, v124
	v_mul_f32_e32 v129, 0x3f4c422a, v129
	v_add_f32_e32 v129, v129, v129
	v_mul_f32_e32 v129, 0x3fb8aa3b, v129
	v_exp_f32_e32 v129, v129
	v_mul_f32_e32 v130, 0x3d372713, v125
	v_mul_f32_e32 v130, v125, v130
	v_fma_f32 v131, v125, v130, v125
	v_add_f32_e32 v129, 1.0, v129
	v_rcp_f32_e32 v130, v129
	v_mul_f32_e32 v129, 0x3f4c422a, v131
	v_mul_f32_e32 v131, 0x3d372713, v126
	v_mul_f32_e32 v131, v126, v131
	s_waitcnt vmcnt(10)
	v_mul_f32_e32 v132, 0x3d372713, v127
	v_fma_f32 v131, v126, v131, v126
	v_mul_f32_e32 v132, v127, v132
	v_mul_f32_e32 v131, 0x3f4c422a, v131
	v_fma_f32 v132, v127, v132, v127
	v_add_f32_e32 v131, v131, v131
	v_mul_f32_e32 v132, 0x3f4c422a, v132
	v_add_f32_e32 v129, v129, v129
	v_mul_f32_e32 v131, 0x3fb8aa3b, v131
	v_add_f32_e32 v132, v132, v132
	v_mul_f32_e32 v129, 0x3fb8aa3b, v129
	v_exp_f32_e32 v131, v131
	v_mul_f32_e32 v132, 0x3fb8aa3b, v132
	v_exp_f32_e32 v129, v129
	v_exp_f32_e32 v133, v132
	v_add_f32_e32 v131, 1.0, v131
	v_rcp_f32_e32 v132, v131
	v_add_f32_e32 v129, 1.0, v129
	v_add_f32_e32 v131, 1.0, v133
	v_rcp_f32_e32 v133, v131
	v_rcp_f32_e32 v131, v129
	v_pk_mul_f32 v[126:127], v[126:127], 0.5 op_sel_hi:[1,0]
	v_pk_mul_f32 v[124:125], v[124:125], 0.5 op_sel_hi:[1,0]
	v_pk_fma_f32 v[132:133], v[132:133], -2.0, 1.0 op_sel_hi:[1,0,0]
	v_pk_fma_f32 v[130:131], v[130:131], -2.0, 1.0 op_sel_hi:[1,0,0]
	v_pk_add_f32 v[132:133], v[132:133], 1.0 op_sel_hi:[1,0]
	v_pk_add_f32 v[130:131], v[130:131], 1.0 op_sel_hi:[1,0]
	v_pk_mul_f32 v[126:127], v[126:127], v[132:133]
	v_pk_mul_f32 v[124:125], v[124:125], v[130:131]
